# v29 plus tile-loop head: direct vmcnt(4) wait on the common path, last-tile vmcnt(0) out of line (one taken branch and three scalar ops fewer per tile)
# speedup vs baseline: 1.0037x; 1.0009x over previous
; __device__ __forceinline__ void attn_unit(const Params& P, int li, LAS unsigned char* lds, int b, int h, int qb, float lam, float one_m_li) {
;     ...
;         const int t = NT - 1 - i;
;         if (t >= 1) asm volatile("s_waitcnt vmcnt(4) lgkmcnt(0)" ::: "memory"); else asm volatile("s_waitcnt vmcnt(0) lgkmcnt(0)" ::: "memory");
;         __builtin_amdgcn_s_barrier();
.LBB0_404:
	s_sub_i32 s4, s35, s21
	s_cmp_lt_i32 s4, 1
	s_cbranch_scc1 .Lattn_last_wait
	s_waitcnt vmcnt(4) lgkmcnt(0)

; __device__ __forceinline__ void attn_unit(const Params& P, int li, LAS unsigned char* lds, int b, int h, int qb, float lam, float one_m_li) {
;     ...
;         if (t >= 1) asm volatile("s_waitcnt vmcnt(4) lgkmcnt(0)" ::: "memory"); else asm volatile("s_waitcnt vmcnt(0) lgkmcnt(0)" ::: "memory");
.Lattn_last_wait:
	s_waitcnt vmcnt(0) lgkmcnt(0)
	s_branch .LBB0_408
